# FNet-prompt epilogue: 16 gate vectors prefetched together; attention item head barrier sunk below the first stage loads
# speedup vs baseline: 1.0124x; 1.0032x over previous
.LBB0_575:
	s_ashr_i32 s23, s23, 1
	s_andn2_b32 s23, s23, 31
	v_and_b32_e32 v190, 31, v4
	s_add_i32 s46, s31, s23
	s_mul_i32 s28, s1, 0x56
	v_or_b32_e32 v0, s46, v190
	s_bfe_u32 s29, s28, 0x1000f
	s_bfe_u32 s28, s28, 0x80008
	v_add_u32_e32 v186, s0, v0
	v_mov_b64_e32 v[6:7], s[24:25]
	s_add_i32 s40, s28, s29
	v_mad_i64_i32 v[188:189], s[28:29], v186, s77, v[6:7]
	s_lshl_b32 s28, s1, 7
	v_bfe_u32 v2, v4, 5, 1
	s_ashr_i32 s29, s28, 31
	v_lshl_add_u64 v[6:7], s[28:29], 1, v[188:189]
	v_lshlrev_b32_e32 v0, 4, v2
	v_lshl_add_u64 v[6:7], v[6:7], 0, v[0:1]
	global_load_dwordx4 v[82:85], v[6:7], off
	global_load_dwordx4 v[86:89], v[6:7], off offset:32
	global_load_dwordx4 v[90:93], v[6:7], off offset:64
	global_load_dwordx4 v[94:97], v[6:7], off offset:96
	global_load_dwordx4 v[98:101], v[6:7], off offset:128
	global_load_dwordx4 v[102:105], v[6:7], off offset:160
	global_load_dwordx4 v[106:109], v[6:7], off offset:192
	global_load_dwordx4 v[110:113], v[6:7], off offset:224
	s_add_i32 s38, s1, s88
	s_ashr_i32 s39, s38, 31
	s_lshl_b64 s[38:39], s[38:39], 2
	v_readlane_b32 s44, v254, 58
	v_readlane_b32 s45, v254, 59
	s_add_u32 s38, s44, s38
	s_addc_u32 s39, s45, s39
	global_load_dword v3, v1, s[38:39]
	s_add_i32 s1, s31, 0x180
	s_min_u32 s1, s36, s1
	s_cmp_lt_i32 s30, 0
	s_sext_i32_i8 s48, s40
	s_cselect_b64 s[40:41], -1, 0
	v_sub_u32_e64 v0, s31, v235 clamp
	s_and_b64 s[38:39], s[40:41], exec
	v_readfirstlane_b32 s23, v0
	s_cselect_b32 s23, 0, s23
	s_cselect_b32 s1, 0x100, s1
	s_sub_i32 s47, s1, s23
	s_ashr_i32 s68, s47, 6
	s_ashr_i32 s1, s0, 31
	s_mul_i32 s38, s0, 0x2800
	s_mul_hi_i32 s31, s0, 0x2800
	s_add_u32 s49, s24, s38
	s_addc_u32 s31, s25, s31
	s_lshl_b32 s38, s48, 7
	s_ashr_i32 s39, s38, 31
	s_lshl_b64 s[44:45], s[38:39], 1
	s_add_u32 s74, s49, s44
	s_addc_u32 s75, s31, s45
	s_lshl_b64 s[0:1], s[0:1], 10
	s_add_u32 s31, s50, s0
	s_addc_u32 s39, s51, s1
	s_mul_hi_i32 s1, s38, s36
	s_mul_i32 s0, s38, s36
	s_lshl_b64 s[0:1], s[0:1], 1
	s_add_u32 s79, s31, s0
	s_addc_u32 s80, s39, s1
	s_max_i32 s30, s30, 0
	s_lshl_b32 s0, s30, 9
	s_or_b32 s60, s0, s63
	s_lshl_b64 s[0:1], s[60:61], 10
	s_add_u32 s0, s54, s0
	s_addc_u32 s1, s55, s1
	s_add_u32 s82, s0, s44
	s_addc_u32 s83, s1, s45
	s_lshl_b32 s0, s30, 3
	s_or_b32 s0, s0, s37
	s_add_i32 s0, s0, s48
	s_lshl_b32 s0, s0, 7
	s_ashr_i32 s1, s0, 31
	s_lshl_b64 s[0:1], s[0:1], 9
	s_add_u32 s84, s18, s0
	s_addc_u32 s85, s19, s1
	s_cmp_lt_i32 s68, 1
	s_mov_b64 s[38:39], -1
	s_cbranch_scc0 .LBB0_577
	s_sub_i32 s60, 0, s47
	s_lshl_b64 s[0:1], s[60:61], 10
	s_add_u32 s0, s82, s0
	s_addc_u32 s1, s83, s1
	s_lshl_b64 s[30:31], s[60:61], 1
	s_add_u32 s30, s84, s30
	s_addc_u32 s31, s85, s31
	s_mov_b64 s[38:39], 0

.LBB0_580:
	v_ashrrev_i32_e32 v191, 4, v4
	v_and_b32_e32 v8, 15, v4
	v_ashrrev_i32_e32 v205, 3, v4
	v_and_b32_e32 v9, 7, v4
	v_mad_i64_i32 v[4:5], s[48:49], s44, v191, 0
	v_lshl_add_u64 v[4:5], v[4:5], 1, s[0:1]
	v_lshlrev_b32_e32 v0, 4, v8
	v_lshl_add_u64 v[4:5], v[4:5], 0, v[0:1]
	global_load_dwordx4 v[114:117], v[4:5], off
	v_mad_i64_i32 v[4:5], s[48:49], s38, v205, 0
	v_lshl_add_u64 v[4:5], v[4:5], 1, s[30:31]
	v_lshlrev_b32_e32 v6, 4, v9
	v_mov_b32_e32 v7, v1
	v_lshl_add_u64 v[4:5], v[4:5], 0, v[6:7]
	v_add_u32_e32 v206, 32, v191
	global_load_dwordx4 v[118:121], v[4:5], off
	v_mad_i64_i32 v[4:5], s[44:45], s44, v206, 0
	v_lshl_add_u64 v[4:5], v[4:5], 1, s[0:1]
	v_lshl_add_u64 v[4:5], v[4:5], 0, v[0:1]
	v_add_u32_e32 v207, 64, v205
	global_load_dwordx4 v[122:125], v[4:5], off
	v_mad_i64_i32 v[4:5], s[0:1], s38, v207, 0
	v_lshl_add_u64 v[4:5], v[4:5], 1, s[30:31]
	v_lshl_add_u64 v[4:5], v[4:5], 0, v[6:7]
	global_load_dwordx4 v[126:129], v[4:5], off
	s_and_b64 s[0:1], s[40:41], exec
	s_movk_i32 s1, 0x88
	v_mul_lo_u32 v5, v205, s1
	s_cselect_b32 s0, 0, 4
	v_mul_lo_u32 v4, v191, s78
	v_add_u32_e32 v5, 0, v5
	s_add_i32 s86, s68, s0
	v_add_u32_e32 v4, 0, v4
	v_add_u32_e32 v211, v5, v6
	v_lshlrev_b32_e32 v208, 3, v8
	v_lshlrev_b32_e32 v209, 3, v9
	v_add_u32_e32 v210, v4, v0
	s_cmp_lt_i32 s86, 2
	v_add_u32_e32 v212, 0x4400, v211
	v_add_u32_e32 v213, 0x6600, v211
	s_waitcnt lgkmcnt(0)
	s_barrier
	s_waitcnt vmcnt(0)
	ds_write_b128 v210, v[114:117]
	ds_write2_b64 v212, v[118:119], v[120:121] offset1:1
	ds_write_b128 v210, v[122:125] offset:8704
	ds_write2_b64 v213, v[126:127], v[128:129] offset1:1
	s_cbranch_scc1 .LBB0_587
	s_cmp_lt_i32 s68, 2
	s_mov_b64 s[38:39], -1
	s_cbranch_scc0 .LBB0_583
	s_sub_i32 s60, 64, s47
	s_lshl_b64 s[0:1], s[60:61], 10
	s_add_u32 s0, s82, s0
	s_addc_u32 s1, s83, s1
	s_lshl_b64 s[30:31], s[60:61], 1
	s_add_u32 s30, s84, s30
	s_addc_u32 s31, s85, s31
	s_mov_b64 s[38:39], 0

.LBB0_725:
	s_lshl_b32 s38, s62, 8
	v_mov_b32_e32 v141, v151
	v_mov_b32_e32 v140, v150
	s_lshl_b32 s30, s62, 7
	s_lshl_b32 s31, s81, 8
	s_and_b32 s38, s38, 0x100
	s_and_b32 s30, s30, 0xffffff00
	s_or_b32 s38, s38, s87
	s_add_i32 s31, s31, s86
	v_lshl_add_u32 v140, v140, 3, s38
	s_add_i32 s31, s31, s30
	v_add_u32_e32 v142, s31, v141
	v_ashrrev_i32_e32 v141, 31, v140
	v_mov_b64_e32 v[144:145], s[24:25]
	v_mad_i64_i32 v[146:147], s[30:31], v142, s77, v[144:145]
	v_lshlrev_b64 v[140:141], 1, v[140:141]
	v_lshl_add_u64 v[146:147], v[146:147], 0, v[140:141]
	v_add_co_u32_e32 v146, vcc, s34, v146
	v_ashrrev_i32_e32 v143, 31, v142
	s_nop 0
	v_addc_co_u32_e32 v147, vcc, 0, v147, vcc
	global_load_dwordx4 v[164:167], v[146:147], off offset:1024
	global_load_dwordx4 v[168:171], v[146:147], off offset:1280
	v_add_co_u32_e32 v162, vcc, 0x28000, v146
	s_nop 1
	v_addc_co_u32_e32 v163, vcc, 0, v147, vcc
	global_load_dwordx4 v[172:175], v[162:163], off offset:1024
	global_load_dwordx4 v[176:179], v[162:163], off offset:1280
	v_add_co_u32_e32 v162, vcc, 0x50000, v146
	s_nop 1
	v_addc_co_u32_e32 v163, vcc, 0, v147, vcc
	global_load_dwordx4 v[180:183], v[162:163], off offset:1024
	global_load_dwordx4 v[184:187], v[162:163], off offset:1280
	v_add_co_u32_e32 v162, vcc, 0x78000, v146
	s_nop 1
	v_addc_co_u32_e32 v163, vcc, 0, v147, vcc
	global_load_dwordx4 v[188:191], v[162:163], off offset:1024
	global_load_dwordx4 v[192:195], v[162:163], off offset:1280
	v_add_co_u32_e32 v162, vcc, 0x140000, v146
	s_nop 1
	v_addc_co_u32_e32 v163, vcc, 0, v147, vcc
	global_load_dwordx4 v[196:199], v[162:163], off offset:1024
	global_load_dwordx4 v[206:209], v[162:163], off offset:1280
	v_add_co_u32_e32 v162, vcc, 0x168000, v146
	s_nop 1
	v_addc_co_u32_e32 v163, vcc, 0, v147, vcc
	global_load_dwordx4 v[210:213], v[162:163], off offset:1024
	global_load_dwordx4 v[214:217], v[162:163], off offset:1280
	v_add_co_u32_e32 v162, vcc, 0x190000, v146
	s_nop 1
	v_addc_co_u32_e32 v163, vcc, 0, v147, vcc
	global_load_dwordx4 v[218:221], v[162:163], off offset:1024
	global_load_dwordx4 v[222:225], v[162:163], off offset:1280
	v_add_co_u32_e32 v162, vcc, 0x1b8000, v146
	s_nop 1
	v_addc_co_u32_e32 v163, vcc, 0, v147, vcc
	global_load_dwordx4 v[226:229], v[162:163], off offset:1024
	global_load_dwordx4 v[230:233], v[162:163], off offset:1280
	v_lshlrev_b64 v[148:149], 12, v[142:143]
	s_waitcnt vmcnt(0)
	v_mov_b32_e32 v154, v164
	v_mov_b32_e32 v155, v165
	v_mov_b32_e32 v156, v166
	v_mov_b32_e32 v157, v167
	v_lshlrev_b32_e32 v158, 16, v154
	v_mul_f32_e32 v143, 0xbfb8aa3b, v158
	v_exp_f32_e32 v143, v143
	v_and_b32_e32 v159, 0xffff0000, v154
	v_lshlrev_b32_e32 v154, 16, v155
	v_and_b32_e32 v155, 0xffff0000, v155
	v_add_f32_e32 v143, 1.0, v143
	v_rcp_f32_e32 v160, v143
	v_mul_f32_e32 v143, 0xbfb8aa3b, v159
	v_exp_f32_e32 v143, v143
	s_nop 0
	v_add_f32_e32 v143, 1.0, v143
	v_rcp_f32_e32 v161, v143
	s_nop 0
	v_pk_mul_f32 v[158:159], v[160:161], v[158:159]
	s_nop 0
	v_pk_mul_f32 v[126:127], v[126:127], v[158:159]
	s_nop 0
	v_cvt_pk_bf16_f32 v126, v126, v127
	v_mul_f32_e32 v127, 0xbfb8aa3b, v154
	v_exp_f32_e32 v127, v127
	s_nop 0
	v_add_f32_e32 v127, 1.0, v127
	v_rcp_f32_e32 v158, v127
	v_mul_f32_e32 v127, 0xbfb8aa3b, v155
	v_exp_f32_e32 v127, v127
	s_nop 0
	v_add_f32_e32 v127, 1.0, v127
	v_rcp_f32_e32 v159, v127
	s_nop 0
	v_pk_mul_f32 v[154:155], v[158:159], v[154:155]
	s_nop 0
	v_pk_mul_f32 v[128:129], v[128:129], v[154:155]
	s_nop 0
	v_cvt_pk_bf16_f32 v127, v128, v129
	v_lshlrev_b32_e32 v128, 16, v156
	v_mul_f32_e32 v143, 0xbfb8aa3b, v128
	v_exp_f32_e32 v143, v143
	v_and_b32_e32 v129, 0xffff0000, v156
	v_add_f32_e32 v143, 1.0, v143
	v_rcp_f32_e32 v154, v143
	v_mul_f32_e32 v143, 0xbfb8aa3b, v129
	v_exp_f32_e32 v143, v143
	s_nop 0
	v_add_f32_e32 v143, 1.0, v143
	v_rcp_f32_e32 v155, v143
	s_nop 0
	v_pk_mul_f32 v[128:129], v[154:155], v[128:129]
	s_nop 0
	v_pk_mul_f32 v[122:123], v[122:123], v[128:129]
	s_nop 0
	v_cvt_pk_bf16_f32 v128, v122, v123
	v_lshlrev_b32_e32 v122, 16, v157
	v_mul_f32_e32 v129, 0xbfb8aa3b, v122
	v_exp_f32_e32 v129, v129
	v_and_b32_e32 v123, 0xffff0000, v157
	v_add_f32_e32 v129, 1.0, v129
	v_rcp_f32_e32 v154, v129
	v_mul_f32_e32 v129, 0xbfb8aa3b, v123
	v_exp_f32_e32 v129, v129
	s_nop 0
	v_add_f32_e32 v129, 1.0, v129
	v_rcp_f32_e32 v155, v129
	s_nop 0
	v_pk_mul_f32 v[122:123], v[154:155], v[122:123]
	s_nop 0
	v_pk_mul_f32 v[122:123], v[124:125], v[122:123]
	s_nop 0
	v_cvt_pk_bf16_f32 v129, v122, v123
	v_lshl_add_u64 v[122:123], s[64:65], 0, v[148:149]
	v_lshl_add_u64 v[122:123], v[122:123], 0, v[140:141]
	global_store_dwordx4 v[122:123], v[126:129], off offset:3072
	v_mov_b32_e32 v124, v168
	v_mov_b32_e32 v125, v169
	v_mov_b32_e32 v126, v170
	v_mov_b32_e32 v127, v171
	v_lshlrev_b32_e32 v128, 16, v124
	v_and_b32_e32 v129, 0xffff0000, v124
	v_mul_f32_e32 v124, 0xbfb8aa3b, v128
	v_exp_f32_e32 v124, v124
	s_nop 0
	v_add_f32_e32 v124, 1.0, v124
	v_rcp_f32_e32 v146, v124
	v_mul_f32_e32 v124, 0xbfb8aa3b, v129
	v_exp_f32_e32 v124, v124
	s_nop 0
	v_add_f32_e32 v124, 1.0, v124
	v_rcp_f32_e32 v147, v124
	v_lshlrev_b32_e32 v124, 16, v125
	v_and_b32_e32 v125, 0xffff0000, v125
	v_pk_mul_f32 v[128:129], v[146:147], v[128:129]
	s_nop 0
	v_pk_mul_f32 v[118:119], v[118:119], v[128:129]
	s_nop 0
	v_cvt_pk_bf16_f32 v118, v118, v119
	v_mul_f32_e32 v119, 0xbfb8aa3b, v124
	v_exp_f32_e32 v119, v119
	s_nop 0
	v_add_f32_e32 v119, 1.0, v119
	v_rcp_f32_e32 v128, v119
	v_mul_f32_e32 v119, 0xbfb8aa3b, v125
	v_exp_f32_e32 v119, v119
	s_nop 0
	v_add_f32_e32 v119, 1.0, v119
	v_rcp_f32_e32 v129, v119
	s_nop 0
	v_pk_mul_f32 v[124:125], v[128:129], v[124:125]
	s_nop 0
	v_pk_mul_f32 v[120:121], v[120:121], v[124:125]
	s_nop 0
	v_cvt_pk_bf16_f32 v119, v120, v121
	v_lshlrev_b32_e32 v120, 16, v126
	v_and_b32_e32 v121, 0xffff0000, v126
	v_mul_f32_e32 v124, 0xbfb8aa3b, v120
	v_mul_f32_e32 v125, 0xbfb8aa3b, v121
	v_exp_f32_e32 v124, v124
	v_exp_f32_e32 v125, v125
	v_add_f32_e32 v124, 1.0, v124
	v_add_f32_e32 v125, 1.0, v125
	v_rcp_f32_e32 v124, v124
	v_rcp_f32_e32 v125, v125
	s_nop 0
	v_pk_mul_f32 v[120:121], v[124:125], v[120:121]
	s_nop 0
	v_pk_mul_f32 v[114:115], v[114:115], v[120:121]
	s_nop 0
	v_cvt_pk_bf16_f32 v120, v114, v115
	v_lshlrev_b32_e32 v114, 16, v127
	v_mul_f32_e32 v121, 0xbfb8aa3b, v114
	v_exp_f32_e32 v121, v121
	v_and_b32_e32 v115, 0xffff0000, v127
	v_add_f32_e32 v121, 1.0, v121
	v_rcp_f32_e32 v124, v121
	v_mul_f32_e32 v121, 0xbfb8aa3b, v115
	v_exp_f32_e32 v121, v121
	s_nop 0
	v_add_f32_e32 v121, 1.0, v121
	v_rcp_f32_e32 v125, v121
	s_nop 0
	v_pk_mul_f32 v[114:115], v[124:125], v[114:115]
	s_nop 0
	v_pk_mul_f32 v[114:115], v[116:117], v[114:115]
	s_nop 0
	v_cvt_pk_bf16_f32 v121, v114, v115
	global_store_dwordx4 v[122:123], v[118:121], off offset:3328
	v_add_u32_e32 v114, 16, v142
	v_ashrrev_i32_e32 v115, 31, v114
	v_lshlrev_b64 v[116:117], 12, v[114:115]
	v_mad_i64_i32 v[114:115], s[30:31], v114, s77, v[144:145]
	v_lshl_add_u64 v[114:115], v[114:115], 0, v[140:141]
	v_add_co_u32_e32 v114, vcc, s34, v114
	s_nop 1
	v_addc_co_u32_e32 v115, vcc, 0, v115, vcc
	v_mov_b32_e32 v118, v172
	v_mov_b32_e32 v119, v173
	v_mov_b32_e32 v120, v174
	v_mov_b32_e32 v121, v175
	v_lshlrev_b32_e32 v122, 16, v118
	v_and_b32_e32 v123, 0xffff0000, v118
	v_mul_f32_e32 v118, 0xbfb8aa3b, v122
	v_exp_f32_e32 v118, v118
	s_nop 0
	v_add_f32_e32 v118, 1.0, v118
	v_rcp_f32_e32 v124, v118
	v_mul_f32_e32 v118, 0xbfb8aa3b, v123
	v_exp_f32_e32 v118, v118
	s_nop 0
	v_add_f32_e32 v118, 1.0, v118
	v_rcp_f32_e32 v125, v118
	v_lshlrev_b32_e32 v118, 16, v119
	v_and_b32_e32 v119, 0xffff0000, v119
	v_pk_mul_f32 v[122:123], v[124:125], v[122:123]
	s_nop 0
	v_pk_mul_f32 v[110:111], v[110:111], v[122:123]
	s_nop 0
	v_cvt_pk_bf16_f32 v110, v110, v111
	v_mul_f32_e32 v111, 0xbfb8aa3b, v118
	v_exp_f32_e32 v111, v111
	s_nop 0
	v_add_f32_e32 v111, 1.0, v111
	v_rcp_f32_e32 v122, v111
	v_mul_f32_e32 v111, 0xbfb8aa3b, v119
	v_exp_f32_e32 v111, v111
	s_nop 0
	v_add_f32_e32 v111, 1.0, v111
	v_rcp_f32_e32 v123, v111
	s_nop 0
	v_pk_mul_f32 v[118:119], v[122:123], v[118:119]
	s_nop 0
	v_pk_mul_f32 v[112:113], v[112:113], v[118:119]
	s_nop 0
	v_cvt_pk_bf16_f32 v111, v112, v113
	v_lshlrev_b32_e32 v112, 16, v120
	v_and_b32_e32 v113, 0xffff0000, v120
	v_mul_f32_e32 v118, 0xbfb8aa3b, v112
	v_mul_f32_e32 v119, 0xbfb8aa3b, v113
	v_exp_f32_e32 v118, v118
	v_exp_f32_e32 v119, v119
	v_add_f32_e32 v118, 1.0, v118
	v_add_f32_e32 v119, 1.0, v119
	v_rcp_f32_e32 v118, v118
	v_rcp_f32_e32 v119, v119
	s_nop 0
	v_pk_mul_f32 v[112:113], v[118:119], v[112:113]
	s_nop 0
	v_pk_mul_f32 v[106:107], v[106:107], v[112:113]
	s_nop 0
	v_cvt_pk_bf16_f32 v112, v106, v107
	v_lshlrev_b32_e32 v106, 16, v121
	v_mul_f32_e32 v113, 0xbfb8aa3b, v106
	v_exp_f32_e32 v113, v113
	v_and_b32_e32 v107, 0xffff0000, v121
	v_add_f32_e32 v113, 1.0, v113
	v_rcp_f32_e32 v118, v113
	v_mul_f32_e32 v113, 0xbfb8aa3b, v107
	v_exp_f32_e32 v113, v113
	s_nop 0
	v_add_f32_e32 v113, 1.0, v113
	v_rcp_f32_e32 v119, v113
	s_nop 0
	v_pk_mul_f32 v[106:107], v[118:119], v[106:107]
	s_nop 0
	v_pk_mul_f32 v[106:107], v[108:109], v[106:107]
	s_nop 0
	v_cvt_pk_bf16_f32 v113, v106, v107
	v_lshl_add_u64 v[106:107], s[64:65], 0, v[116:117]
	v_lshl_add_u64 v[106:107], v[106:107], 0, v[140:141]
	global_store_dwordx4 v[106:107], v[110:113], off offset:3072
	v_mov_b32_e32 v108, v176
	v_mov_b32_e32 v109, v177
	v_mov_b32_e32 v110, v178
	v_mov_b32_e32 v111, v179
	v_lshlrev_b32_e32 v112, 16, v108
	v_and_b32_e32 v113, 0xffff0000, v108
	v_mul_f32_e32 v108, 0xbfb8aa3b, v112
	v_exp_f32_e32 v108, v108
	s_nop 0
	v_add_f32_e32 v108, 1.0, v108
	v_rcp_f32_e32 v114, v108
	v_mul_f32_e32 v108, 0xbfb8aa3b, v113
	v_exp_f32_e32 v108, v108
	s_nop 0
	v_add_f32_e32 v108, 1.0, v108
	v_rcp_f32_e32 v115, v108
	v_lshlrev_b32_e32 v108, 16, v109
	v_and_b32_e32 v109, 0xffff0000, v109
	v_pk_mul_f32 v[112:113], v[114:115], v[112:113]
	s_nop 0
	v_pk_mul_f32 v[102:103], v[102:103], v[112:113]
	s_nop 0
	v_cvt_pk_bf16_f32 v102, v102, v103
	v_mul_f32_e32 v103, 0xbfb8aa3b, v108
	v_exp_f32_e32 v103, v103
	s_nop 0
	v_add_f32_e32 v103, 1.0, v103
	v_rcp_f32_e32 v112, v103
	v_mul_f32_e32 v103, 0xbfb8aa3b, v109
	v_exp_f32_e32 v103, v103
	s_nop 0
	v_add_f32_e32 v103, 1.0, v103
	v_rcp_f32_e32 v113, v103
	s_nop 0
	v_pk_mul_f32 v[108:109], v[112:113], v[108:109]
	s_nop 0
	v_pk_mul_f32 v[104:105], v[104:105], v[108:109]
	s_nop 0
	v_cvt_pk_bf16_f32 v103, v104, v105
	v_lshlrev_b32_e32 v104, 16, v110
	v_and_b32_e32 v105, 0xffff0000, v110
	v_mul_f32_e32 v108, 0xbfb8aa3b, v104
	v_mul_f32_e32 v109, 0xbfb8aa3b, v105
	v_exp_f32_e32 v108, v108
	v_exp_f32_e32 v109, v109
	v_add_f32_e32 v108, 1.0, v108
	v_add_f32_e32 v109, 1.0, v109
	v_rcp_f32_e32 v108, v108
	v_rcp_f32_e32 v109, v109
	s_nop 0
	v_pk_mul_f32 v[104:105], v[108:109], v[104:105]
	s_nop 0
	v_pk_mul_f32 v[98:99], v[98:99], v[104:105]
	s_nop 0
	v_cvt_pk_bf16_f32 v104, v98, v99
	v_lshlrev_b32_e32 v98, 16, v111
	v_mul_f32_e32 v105, 0xbfb8aa3b, v98
	v_exp_f32_e32 v105, v105
	v_and_b32_e32 v99, 0xffff0000, v111
	v_add_f32_e32 v105, 1.0, v105
	v_rcp_f32_e32 v108, v105
	v_mul_f32_e32 v105, 0xbfb8aa3b, v99
	v_exp_f32_e32 v105, v105
	s_nop 0
	v_add_f32_e32 v105, 1.0, v105
	v_rcp_f32_e32 v109, v105
	s_nop 0
	v_pk_mul_f32 v[98:99], v[108:109], v[98:99]
	s_nop 0
	v_pk_mul_f32 v[98:99], v[100:101], v[98:99]
	s_nop 0
	v_cvt_pk_bf16_f32 v105, v98, v99
	global_store_dwordx4 v[106:107], v[102:105], off offset:3328
	v_add_u32_e32 v98, 32, v142
	v_ashrrev_i32_e32 v99, 31, v98
	v_lshlrev_b64 v[100:101], 12, v[98:99]
	v_mad_i64_i32 v[98:99], s[30:31], v98, s77, v[144:145]
	v_lshl_add_u64 v[98:99], v[98:99], 0, v[140:141]
	v_add_co_u32_e32 v98, vcc, s34, v98
	s_nop 1
	v_addc_co_u32_e32 v99, vcc, 0, v99, vcc
	v_mov_b32_e32 v102, v180
	v_mov_b32_e32 v103, v181
	v_mov_b32_e32 v104, v182
	v_mov_b32_e32 v105, v183
	v_lshlrev_b32_e32 v106, 16, v102
	v_and_b32_e32 v107, 0xffff0000, v102
	v_mul_f32_e32 v102, 0xbfb8aa3b, v106
	v_exp_f32_e32 v102, v102
	s_nop 0
	v_add_f32_e32 v102, 1.0, v102
	v_rcp_f32_e32 v108, v102
	v_mul_f32_e32 v102, 0xbfb8aa3b, v107
	v_exp_f32_e32 v102, v102
	s_nop 0
	v_add_f32_e32 v102, 1.0, v102
	v_rcp_f32_e32 v109, v102
	v_lshlrev_b32_e32 v102, 16, v103
	v_and_b32_e32 v103, 0xffff0000, v103
	v_pk_mul_f32 v[106:107], v[108:109], v[106:107]
	s_nop 0
	v_pk_mul_f32 v[94:95], v[94:95], v[106:107]
	s_nop 0
	v_cvt_pk_bf16_f32 v94, v94, v95
	v_mul_f32_e32 v95, 0xbfb8aa3b, v102
	v_exp_f32_e32 v95, v95
	s_nop 0
	v_add_f32_e32 v95, 1.0, v95
	v_rcp_f32_e32 v106, v95
	v_mul_f32_e32 v95, 0xbfb8aa3b, v103
	v_exp_f32_e32 v95, v95
	s_nop 0
	v_add_f32_e32 v95, 1.0, v95
	v_rcp_f32_e32 v107, v95
	s_nop 0
	v_pk_mul_f32 v[102:103], v[106:107], v[102:103]
	s_nop 0
	v_pk_mul_f32 v[96:97], v[96:97], v[102:103]
	s_nop 0
	v_cvt_pk_bf16_f32 v95, v96, v97
	v_lshlrev_b32_e32 v96, 16, v104
	v_and_b32_e32 v97, 0xffff0000, v104
	v_mul_f32_e32 v102, 0xbfb8aa3b, v96
	v_mul_f32_e32 v103, 0xbfb8aa3b, v97
	v_exp_f32_e32 v102, v102
	v_exp_f32_e32 v103, v103
	v_add_f32_e32 v102, 1.0, v102
	v_add_f32_e32 v103, 1.0, v103
	v_rcp_f32_e32 v102, v102
	v_rcp_f32_e32 v103, v103
	s_nop 0
	v_pk_mul_f32 v[96:97], v[102:103], v[96:97]
	s_nop 0
	v_pk_mul_f32 v[90:91], v[90:91], v[96:97]
	s_nop 0
	v_cvt_pk_bf16_f32 v96, v90, v91
	v_lshlrev_b32_e32 v90, 16, v105
	v_mul_f32_e32 v97, 0xbfb8aa3b, v90
	v_exp_f32_e32 v97, v97
	v_and_b32_e32 v91, 0xffff0000, v105
	v_add_f32_e32 v97, 1.0, v97
	v_rcp_f32_e32 v102, v97
	v_mul_f32_e32 v97, 0xbfb8aa3b, v91
	v_exp_f32_e32 v97, v97
	s_nop 0
	v_add_f32_e32 v97, 1.0, v97
	v_rcp_f32_e32 v103, v97
	s_nop 0
	v_pk_mul_f32 v[90:91], v[102:103], v[90:91]
	s_nop 0
	v_pk_mul_f32 v[90:91], v[92:93], v[90:91]
	s_nop 0
	v_cvt_pk_bf16_f32 v97, v90, v91
	v_lshl_add_u64 v[90:91], s[64:65], 0, v[100:101]
	v_lshl_add_u64 v[90:91], v[90:91], 0, v[140:141]
	global_store_dwordx4 v[90:91], v[94:97], off offset:3072
	v_mov_b32_e32 v92, v184
	v_mov_b32_e32 v93, v185
	v_mov_b32_e32 v94, v186
	v_mov_b32_e32 v95, v187
	v_lshlrev_b32_e32 v96, 16, v92
	v_and_b32_e32 v97, 0xffff0000, v92
	v_mul_f32_e32 v92, 0xbfb8aa3b, v96
	v_exp_f32_e32 v92, v92
	s_nop 0
	v_add_f32_e32 v92, 1.0, v92
	v_rcp_f32_e32 v98, v92
	v_mul_f32_e32 v92, 0xbfb8aa3b, v97
	v_exp_f32_e32 v92, v92
	s_nop 0
	v_add_f32_e32 v92, 1.0, v92
	v_rcp_f32_e32 v99, v92
	v_lshlrev_b32_e32 v92, 16, v93
	v_and_b32_e32 v93, 0xffff0000, v93
	v_pk_mul_f32 v[96:97], v[98:99], v[96:97]
	s_nop 0
	v_pk_mul_f32 v[86:87], v[86:87], v[96:97]
	s_nop 0
	v_cvt_pk_bf16_f32 v86, v86, v87
	v_mul_f32_e32 v87, 0xbfb8aa3b, v92
	v_exp_f32_e32 v87, v87
	s_nop 0
	v_add_f32_e32 v87, 1.0, v87
	v_rcp_f32_e32 v96, v87
	v_mul_f32_e32 v87, 0xbfb8aa3b, v93
	v_exp_f32_e32 v87, v87
	s_nop 0
	v_add_f32_e32 v87, 1.0, v87
	v_rcp_f32_e32 v97, v87
	s_nop 0
	v_pk_mul_f32 v[92:93], v[96:97], v[92:93]
	s_nop 0
	v_pk_mul_f32 v[88:89], v[88:89], v[92:93]
	s_nop 0
	v_cvt_pk_bf16_f32 v87, v88, v89
	v_lshlrev_b32_e32 v88, 16, v94
	v_and_b32_e32 v89, 0xffff0000, v94
	v_mul_f32_e32 v92, 0xbfb8aa3b, v88
	v_mul_f32_e32 v93, 0xbfb8aa3b, v89
	v_exp_f32_e32 v92, v92
	v_exp_f32_e32 v93, v93
	v_add_f32_e32 v92, 1.0, v92
	v_add_f32_e32 v93, 1.0, v93
	v_rcp_f32_e32 v92, v92
	v_rcp_f32_e32 v93, v93
	s_nop 0
	v_pk_mul_f32 v[88:89], v[92:93], v[88:89]
	s_nop 0
	v_pk_mul_f32 v[82:83], v[82:83], v[88:89]
	s_nop 0
	v_cvt_pk_bf16_f32 v88, v82, v83
	v_lshlrev_b32_e32 v82, 16, v95
	v_mul_f32_e32 v89, 0xbfb8aa3b, v82
	v_exp_f32_e32 v89, v89
	v_and_b32_e32 v83, 0xffff0000, v95
	v_add_f32_e32 v89, 1.0, v89
	v_rcp_f32_e32 v92, v89
	v_mul_f32_e32 v89, 0xbfb8aa3b, v83
	v_exp_f32_e32 v89, v89
	s_nop 0
	v_add_f32_e32 v89, 1.0, v89
	v_rcp_f32_e32 v93, v89
	s_nop 0
	v_pk_mul_f32 v[82:83], v[92:93], v[82:83]
	s_nop 0
	v_pk_mul_f32 v[82:83], v[84:85], v[82:83]
	s_nop 0
	v_cvt_pk_bf16_f32 v89, v82, v83
	global_store_dwordx4 v[90:91], v[86:89], off offset:3328
	v_add_u32_e32 v82, 48, v142
	v_ashrrev_i32_e32 v83, 31, v82
	v_lshlrev_b64 v[84:85], 12, v[82:83]
	v_mad_i64_i32 v[82:83], s[30:31], v82, s77, v[144:145]
	v_lshl_add_u64 v[82:83], v[82:83], 0, v[140:141]
	v_add_co_u32_e32 v82, vcc, s34, v82
	s_nop 1
	v_addc_co_u32_e32 v83, vcc, 0, v83, vcc
	v_mov_b32_e32 v86, v188
	v_mov_b32_e32 v87, v189
	v_mov_b32_e32 v88, v190
	v_mov_b32_e32 v89, v191
	v_lshlrev_b32_e32 v90, 16, v86
	v_and_b32_e32 v91, 0xffff0000, v86
	v_mul_f32_e32 v86, 0xbfb8aa3b, v90
	v_exp_f32_e32 v86, v86
	s_nop 0
	v_add_f32_e32 v86, 1.0, v86
	v_rcp_f32_e32 v92, v86
	v_mul_f32_e32 v86, 0xbfb8aa3b, v91
	v_exp_f32_e32 v86, v86
	s_nop 0
	v_add_f32_e32 v86, 1.0, v86
	v_rcp_f32_e32 v93, v86
	v_lshlrev_b32_e32 v86, 16, v87
	v_and_b32_e32 v87, 0xffff0000, v87
	v_pk_mul_f32 v[90:91], v[92:93], v[90:91]
	s_nop 0
	v_pk_mul_f32 v[78:79], v[78:79], v[90:91]
	s_nop 0
	v_cvt_pk_bf16_f32 v78, v78, v79
	v_mul_f32_e32 v79, 0xbfb8aa3b, v86
	v_exp_f32_e32 v79, v79
	s_nop 0
	v_add_f32_e32 v79, 1.0, v79
	v_rcp_f32_e32 v90, v79
	v_mul_f32_e32 v79, 0xbfb8aa3b, v87
	v_exp_f32_e32 v79, v79
	s_nop 0
	v_add_f32_e32 v79, 1.0, v79
	v_rcp_f32_e32 v91, v79
	s_nop 0
	v_pk_mul_f32 v[86:87], v[90:91], v[86:87]
	s_nop 0
	v_pk_mul_f32 v[80:81], v[80:81], v[86:87]
	s_nop 0
	v_cvt_pk_bf16_f32 v79, v80, v81
	v_lshlrev_b32_e32 v80, 16, v88
	v_and_b32_e32 v81, 0xffff0000, v88
	v_mul_f32_e32 v86, 0xbfb8aa3b, v80
	v_mul_f32_e32 v87, 0xbfb8aa3b, v81
	v_exp_f32_e32 v86, v86
	v_exp_f32_e32 v87, v87
	v_add_f32_e32 v86, 1.0, v86
	v_add_f32_e32 v87, 1.0, v87
	v_rcp_f32_e32 v86, v86
	v_rcp_f32_e32 v87, v87
	s_nop 0
	v_pk_mul_f32 v[80:81], v[86:87], v[80:81]
	s_nop 0
	v_pk_mul_f32 v[74:75], v[74:75], v[80:81]
	s_nop 0
	v_cvt_pk_bf16_f32 v80, v74, v75
	v_lshlrev_b32_e32 v74, 16, v89
	v_mul_f32_e32 v81, 0xbfb8aa3b, v74
	v_exp_f32_e32 v81, v81
	v_and_b32_e32 v75, 0xffff0000, v89
	v_add_f32_e32 v81, 1.0, v81
	v_rcp_f32_e32 v86, v81
	v_mul_f32_e32 v81, 0xbfb8aa3b, v75
	v_exp_f32_e32 v81, v81
	s_nop 0
	v_add_f32_e32 v81, 1.0, v81
	v_rcp_f32_e32 v87, v81
	s_nop 0
	v_pk_mul_f32 v[74:75], v[86:87], v[74:75]
	s_nop 0
	v_pk_mul_f32 v[74:75], v[76:77], v[74:75]
	s_nop 0
	v_cvt_pk_bf16_f32 v81, v74, v75
	v_lshl_add_u64 v[74:75], s[64:65], 0, v[84:85]
	v_lshl_add_u64 v[74:75], v[74:75], 0, v[140:141]
	global_store_dwordx4 v[74:75], v[78:81], off offset:3072
	v_mov_b32_e32 v76, v192
	v_mov_b32_e32 v77, v193
	v_mov_b32_e32 v78, v194
	v_mov_b32_e32 v79, v195
	v_lshlrev_b32_e32 v80, 16, v76
	v_and_b32_e32 v81, 0xffff0000, v76
	v_mul_f32_e32 v76, 0xbfb8aa3b, v80
	v_exp_f32_e32 v76, v76
	s_nop 0
	v_add_f32_e32 v76, 1.0, v76
	v_rcp_f32_e32 v82, v76
	v_mul_f32_e32 v76, 0xbfb8aa3b, v81
	v_exp_f32_e32 v76, v76
	s_nop 0
	v_add_f32_e32 v76, 1.0, v76
	v_rcp_f32_e32 v83, v76
	v_lshlrev_b32_e32 v76, 16, v77
	v_and_b32_e32 v77, 0xffff0000, v77
	v_pk_mul_f32 v[80:81], v[82:83], v[80:81]
	s_nop 0
	v_pk_mul_f32 v[70:71], v[70:71], v[80:81]
	s_nop 0
	v_cvt_pk_bf16_f32 v70, v70, v71
	v_mul_f32_e32 v71, 0xbfb8aa3b, v76
	v_exp_f32_e32 v71, v71
	s_nop 0
	v_add_f32_e32 v71, 1.0, v71
	v_rcp_f32_e32 v80, v71
	v_mul_f32_e32 v71, 0xbfb8aa3b, v77
	v_exp_f32_e32 v71, v71
	s_nop 0
	v_add_f32_e32 v71, 1.0, v71
	v_rcp_f32_e32 v81, v71
	s_nop 0
	v_pk_mul_f32 v[76:77], v[80:81], v[76:77]
	s_nop 0
	v_pk_mul_f32 v[72:73], v[72:73], v[76:77]
	s_nop 0
	v_cvt_pk_bf16_f32 v71, v72, v73
	v_lshlrev_b32_e32 v72, 16, v78
	v_and_b32_e32 v73, 0xffff0000, v78
	v_mul_f32_e32 v76, 0xbfb8aa3b, v72
	v_mul_f32_e32 v77, 0xbfb8aa3b, v73
	v_exp_f32_e32 v76, v76
	v_exp_f32_e32 v77, v77
	v_add_f32_e32 v76, 1.0, v76
	v_add_f32_e32 v77, 1.0, v77
	v_rcp_f32_e32 v76, v76
	v_rcp_f32_e32 v77, v77
	s_nop 0
	v_pk_mul_f32 v[72:73], v[76:77], v[72:73]
	s_nop 0
	v_pk_mul_f32 v[66:67], v[66:67], v[72:73]
	s_nop 0
	v_cvt_pk_bf16_f32 v72, v66, v67
	v_lshlrev_b32_e32 v66, 16, v79
	v_mul_f32_e32 v73, 0xbfb8aa3b, v66
	v_exp_f32_e32 v73, v73
	v_and_b32_e32 v67, 0xffff0000, v79
	v_add_f32_e32 v73, 1.0, v73
	v_rcp_f32_e32 v76, v73
	v_mul_f32_e32 v73, 0xbfb8aa3b, v67
	v_exp_f32_e32 v73, v73
	s_nop 0
	v_add_f32_e32 v73, 1.0, v73
	v_rcp_f32_e32 v77, v73
	s_nop 0
	v_pk_mul_f32 v[66:67], v[76:77], v[66:67]
	s_nop 0
	v_pk_mul_f32 v[66:67], v[68:69], v[66:67]
	s_nop 0
	v_cvt_pk_bf16_f32 v73, v66, v67
	global_store_dwordx4 v[74:75], v[70:73], off offset:3328
	v_add_u32_e32 v66, 0x80, v142
	v_ashrrev_i32_e32 v67, 31, v66
	v_lshlrev_b64 v[68:69], 12, v[66:67]
	v_mad_i64_i32 v[66:67], s[30:31], v66, s77, v[144:145]
	v_lshl_add_u64 v[66:67], v[66:67], 0, v[140:141]
	v_add_co_u32_e32 v66, vcc, s34, v66
	s_nop 1
	v_addc_co_u32_e32 v67, vcc, 0, v67, vcc
	v_mov_b32_e32 v70, v196
	v_mov_b32_e32 v71, v197
	v_mov_b32_e32 v72, v198
	v_mov_b32_e32 v73, v199
	v_lshlrev_b32_e32 v74, 16, v70
	v_and_b32_e32 v75, 0xffff0000, v70
	v_mul_f32_e32 v70, 0xbfb8aa3b, v74
	v_exp_f32_e32 v70, v70
	s_nop 0
	v_add_f32_e32 v70, 1.0, v70
	v_rcp_f32_e32 v76, v70
	v_mul_f32_e32 v70, 0xbfb8aa3b, v75
	v_exp_f32_e32 v70, v70
	s_nop 0
	v_add_f32_e32 v70, 1.0, v70
	v_rcp_f32_e32 v77, v70
	v_lshlrev_b32_e32 v70, 16, v71
	v_and_b32_e32 v71, 0xffff0000, v71
	v_pk_mul_f32 v[74:75], v[76:77], v[74:75]
	s_nop 0
	v_pk_mul_f32 v[62:63], v[62:63], v[74:75]
	s_nop 0
	v_cvt_pk_bf16_f32 v62, v62, v63
	v_mul_f32_e32 v63, 0xbfb8aa3b, v70
	v_exp_f32_e32 v63, v63
	s_nop 0
	v_add_f32_e32 v63, 1.0, v63
	v_rcp_f32_e32 v74, v63
	v_mul_f32_e32 v63, 0xbfb8aa3b, v71
	v_exp_f32_e32 v63, v63
	s_nop 0
	v_add_f32_e32 v63, 1.0, v63
	v_rcp_f32_e32 v75, v63
	s_nop 0
	v_pk_mul_f32 v[70:71], v[74:75], v[70:71]
	s_nop 0
	v_pk_mul_f32 v[64:65], v[64:65], v[70:71]
	s_nop 0
	v_cvt_pk_bf16_f32 v63, v64, v65
	v_lshlrev_b32_e32 v64, 16, v72
	v_and_b32_e32 v65, 0xffff0000, v72
	v_mul_f32_e32 v70, 0xbfb8aa3b, v64
	v_mul_f32_e32 v71, 0xbfb8aa3b, v65
	v_exp_f32_e32 v70, v70
	v_exp_f32_e32 v71, v71
	v_add_f32_e32 v70, 1.0, v70
	v_add_f32_e32 v71, 1.0, v71
	v_rcp_f32_e32 v70, v70
	v_rcp_f32_e32 v71, v71
	s_nop 0
	v_pk_mul_f32 v[64:65], v[70:71], v[64:65]
	s_nop 0
	v_pk_mul_f32 v[58:59], v[58:59], v[64:65]
	s_nop 0
	v_cvt_pk_bf16_f32 v64, v58, v59
	v_lshlrev_b32_e32 v58, 16, v73
	v_mul_f32_e32 v65, 0xbfb8aa3b, v58
	v_exp_f32_e32 v65, v65
	v_and_b32_e32 v59, 0xffff0000, v73
	v_add_f32_e32 v65, 1.0, v65
	v_rcp_f32_e32 v70, v65
	v_mul_f32_e32 v65, 0xbfb8aa3b, v59
	v_exp_f32_e32 v65, v65
	s_nop 0
	v_add_f32_e32 v65, 1.0, v65
	v_rcp_f32_e32 v71, v65
	s_nop 0
	v_pk_mul_f32 v[58:59], v[70:71], v[58:59]
	s_nop 0
	v_pk_mul_f32 v[58:59], v[60:61], v[58:59]
	s_nop 0
	v_cvt_pk_bf16_f32 v65, v58, v59
	v_lshl_add_u64 v[58:59], s[64:65], 0, v[68:69]
	v_lshl_add_u64 v[58:59], v[58:59], 0, v[140:141]
	global_store_dwordx4 v[58:59], v[62:65], off offset:3072
	v_mov_b32_e32 v60, v206
	v_mov_b32_e32 v61, v207
	v_mov_b32_e32 v62, v208
	v_mov_b32_e32 v63, v209
	v_lshlrev_b32_e32 v64, 16, v60
	v_and_b32_e32 v65, 0xffff0000, v60
	v_mul_f32_e32 v60, 0xbfb8aa3b, v64
	v_exp_f32_e32 v60, v60
	s_nop 0
	v_add_f32_e32 v60, 1.0, v60
	v_rcp_f32_e32 v66, v60
	v_mul_f32_e32 v60, 0xbfb8aa3b, v65
	v_exp_f32_e32 v60, v60
	s_nop 0
	v_add_f32_e32 v60, 1.0, v60
	v_rcp_f32_e32 v67, v60
	v_lshlrev_b32_e32 v60, 16, v61
	v_and_b32_e32 v61, 0xffff0000, v61
	v_pk_mul_f32 v[64:65], v[66:67], v[64:65]
	s_nop 0
	v_pk_mul_f32 v[54:55], v[54:55], v[64:65]
	s_nop 0
	v_cvt_pk_bf16_f32 v54, v54, v55
	v_mul_f32_e32 v55, 0xbfb8aa3b, v60
	v_exp_f32_e32 v55, v55
	s_nop 0
	v_add_f32_e32 v55, 1.0, v55
	v_rcp_f32_e32 v64, v55
	v_mul_f32_e32 v55, 0xbfb8aa3b, v61
	v_exp_f32_e32 v55, v55
	s_nop 0
	v_add_f32_e32 v55, 1.0, v55
	v_rcp_f32_e32 v65, v55
	s_nop 0
	v_pk_mul_f32 v[60:61], v[64:65], v[60:61]
	s_nop 0
	v_pk_mul_f32 v[56:57], v[56:57], v[60:61]
	s_nop 0
	v_cvt_pk_bf16_f32 v55, v56, v57
	v_lshlrev_b32_e32 v56, 16, v62
	v_and_b32_e32 v57, 0xffff0000, v62
	v_mul_f32_e32 v60, 0xbfb8aa3b, v56
	v_mul_f32_e32 v61, 0xbfb8aa3b, v57
	v_exp_f32_e32 v60, v60
	v_exp_f32_e32 v61, v61
	v_add_f32_e32 v60, 1.0, v60
	v_add_f32_e32 v61, 1.0, v61
	v_rcp_f32_e32 v60, v60
	v_rcp_f32_e32 v61, v61
	s_nop 0
	v_pk_mul_f32 v[56:57], v[60:61], v[56:57]
	s_nop 0
	v_pk_mul_f32 v[50:51], v[50:51], v[56:57]
	s_nop 0
	v_cvt_pk_bf16_f32 v56, v50, v51
	v_lshlrev_b32_e32 v50, 16, v63
	v_mul_f32_e32 v57, 0xbfb8aa3b, v50
	v_exp_f32_e32 v57, v57
	v_and_b32_e32 v51, 0xffff0000, v63
	v_add_f32_e32 v57, 1.0, v57
	v_rcp_f32_e32 v60, v57
	v_mul_f32_e32 v57, 0xbfb8aa3b, v51
	v_exp_f32_e32 v57, v57
	s_nop 0
	v_add_f32_e32 v57, 1.0, v57
	v_rcp_f32_e32 v61, v57
	s_nop 0
	v_pk_mul_f32 v[50:51], v[60:61], v[50:51]
	s_nop 0
	v_pk_mul_f32 v[50:51], v[52:53], v[50:51]
	s_nop 0
	v_cvt_pk_bf16_f32 v57, v50, v51
	global_store_dwordx4 v[58:59], v[54:57], off offset:3328
	v_add_u32_e32 v50, 0x90, v142
	v_ashrrev_i32_e32 v51, 31, v50
	v_lshlrev_b64 v[52:53], 12, v[50:51]
	v_mad_i64_i32 v[50:51], s[30:31], v50, s77, v[144:145]
	v_lshl_add_u64 v[50:51], v[50:51], 0, v[140:141]
	v_add_co_u32_e32 v50, vcc, s34, v50
	s_nop 1
	v_addc_co_u32_e32 v51, vcc, 0, v51, vcc
	v_mov_b32_e32 v54, v210
	v_mov_b32_e32 v55, v211
	v_mov_b32_e32 v56, v212
	v_mov_b32_e32 v57, v213
	v_lshlrev_b32_e32 v58, 16, v54
	v_and_b32_e32 v59, 0xffff0000, v54
	v_mul_f32_e32 v54, 0xbfb8aa3b, v58
	v_exp_f32_e32 v54, v54
	s_nop 0
	v_add_f32_e32 v54, 1.0, v54
	v_rcp_f32_e32 v60, v54
	v_mul_f32_e32 v54, 0xbfb8aa3b, v59
	v_exp_f32_e32 v54, v54
	s_nop 0
	v_add_f32_e32 v54, 1.0, v54
	v_rcp_f32_e32 v61, v54
	v_lshlrev_b32_e32 v54, 16, v55
	v_and_b32_e32 v55, 0xffff0000, v55
	v_pk_mul_f32 v[58:59], v[60:61], v[58:59]
	s_nop 0
	v_pk_mul_f32 v[46:47], v[46:47], v[58:59]
	s_nop 0
	v_cvt_pk_bf16_f32 v46, v46, v47
	v_mul_f32_e32 v47, 0xbfb8aa3b, v54
	v_exp_f32_e32 v47, v47
	s_nop 0
	v_add_f32_e32 v47, 1.0, v47
	v_rcp_f32_e32 v58, v47
	v_mul_f32_e32 v47, 0xbfb8aa3b, v55
	v_exp_f32_e32 v47, v47
	s_nop 0
	v_add_f32_e32 v47, 1.0, v47
	v_rcp_f32_e32 v59, v47
	s_nop 0
	v_pk_mul_f32 v[54:55], v[58:59], v[54:55]
	s_nop 0
	v_pk_mul_f32 v[48:49], v[48:49], v[54:55]
	s_nop 0
	v_cvt_pk_bf16_f32 v47, v48, v49
	v_lshlrev_b32_e32 v48, 16, v56
	v_and_b32_e32 v49, 0xffff0000, v56
	v_mul_f32_e32 v54, 0xbfb8aa3b, v48
	v_mul_f32_e32 v55, 0xbfb8aa3b, v49
	v_exp_f32_e32 v54, v54
	v_exp_f32_e32 v55, v55
	v_add_f32_e32 v54, 1.0, v54
	v_add_f32_e32 v55, 1.0, v55
	v_rcp_f32_e32 v54, v54
	v_rcp_f32_e32 v55, v55
	s_nop 0
	v_pk_mul_f32 v[48:49], v[54:55], v[48:49]
	s_nop 0
	v_pk_mul_f32 v[42:43], v[42:43], v[48:49]
	s_nop 0
	v_cvt_pk_bf16_f32 v48, v42, v43
	v_lshlrev_b32_e32 v42, 16, v57
	v_mul_f32_e32 v49, 0xbfb8aa3b, v42
	v_exp_f32_e32 v49, v49
	v_and_b32_e32 v43, 0xffff0000, v57
	v_add_f32_e32 v49, 1.0, v49
	v_rcp_f32_e32 v54, v49
	v_mul_f32_e32 v49, 0xbfb8aa3b, v43
	v_exp_f32_e32 v49, v49
	s_nop 0
	v_add_f32_e32 v49, 1.0, v49
	v_rcp_f32_e32 v55, v49
	s_nop 0
	v_pk_mul_f32 v[42:43], v[54:55], v[42:43]
	s_nop 0
	v_pk_mul_f32 v[42:43], v[44:45], v[42:43]
	s_nop 0
	v_cvt_pk_bf16_f32 v49, v42, v43
	v_lshl_add_u64 v[42:43], s[64:65], 0, v[52:53]
	v_lshl_add_u64 v[42:43], v[42:43], 0, v[140:141]
	global_store_dwordx4 v[42:43], v[46:49], off offset:3072
	v_mov_b32_e32 v44, v214
	v_mov_b32_e32 v45, v215
	v_mov_b32_e32 v46, v216
	v_mov_b32_e32 v47, v217
	v_lshlrev_b32_e32 v48, 16, v44
	v_and_b32_e32 v49, 0xffff0000, v44
	v_mul_f32_e32 v44, 0xbfb8aa3b, v48
	v_exp_f32_e32 v44, v44
	s_nop 0
	v_add_f32_e32 v44, 1.0, v44
	v_rcp_f32_e32 v50, v44
	v_mul_f32_e32 v44, 0xbfb8aa3b, v49
	v_exp_f32_e32 v44, v44
	s_nop 0
	v_add_f32_e32 v44, 1.0, v44
	v_rcp_f32_e32 v51, v44
	v_lshlrev_b32_e32 v44, 16, v45
	v_and_b32_e32 v45, 0xffff0000, v45
	v_pk_mul_f32 v[48:49], v[50:51], v[48:49]
	s_nop 0
	v_pk_mul_f32 v[38:39], v[38:39], v[48:49]
	s_nop 0
	v_cvt_pk_bf16_f32 v38, v38, v39
	v_mul_f32_e32 v39, 0xbfb8aa3b, v44
	v_exp_f32_e32 v39, v39
	s_nop 0
	v_add_f32_e32 v39, 1.0, v39
	v_rcp_f32_e32 v48, v39
	v_mul_f32_e32 v39, 0xbfb8aa3b, v45
	v_exp_f32_e32 v39, v39
	s_nop 0
	v_add_f32_e32 v39, 1.0, v39
	v_rcp_f32_e32 v49, v39
	s_nop 0
	v_pk_mul_f32 v[44:45], v[48:49], v[44:45]
	s_nop 0
	v_pk_mul_f32 v[40:41], v[40:41], v[44:45]
	s_nop 0
	v_cvt_pk_bf16_f32 v39, v40, v41
	v_lshlrev_b32_e32 v40, 16, v46
	v_and_b32_e32 v41, 0xffff0000, v46
	v_mul_f32_e32 v44, 0xbfb8aa3b, v40
	v_mul_f32_e32 v45, 0xbfb8aa3b, v41
	v_exp_f32_e32 v44, v44
	v_exp_f32_e32 v45, v45
	v_add_f32_e32 v44, 1.0, v44
	v_add_f32_e32 v45, 1.0, v45
	v_rcp_f32_e32 v44, v44
	v_rcp_f32_e32 v45, v45
	s_nop 0
	v_pk_mul_f32 v[40:41], v[44:45], v[40:41]
	s_nop 0
	v_pk_mul_f32 v[34:35], v[34:35], v[40:41]
	s_nop 0
	v_cvt_pk_bf16_f32 v40, v34, v35
	v_lshlrev_b32_e32 v34, 16, v47
	v_mul_f32_e32 v41, 0xbfb8aa3b, v34
	v_exp_f32_e32 v41, v41
	v_and_b32_e32 v35, 0xffff0000, v47
	v_add_f32_e32 v41, 1.0, v41
	v_rcp_f32_e32 v44, v41
	v_mul_f32_e32 v41, 0xbfb8aa3b, v35
	v_exp_f32_e32 v41, v41
	s_nop 0
	v_add_f32_e32 v41, 1.0, v41
	v_rcp_f32_e32 v45, v41
	s_nop 0
	v_pk_mul_f32 v[34:35], v[44:45], v[34:35]
	s_nop 0
	v_pk_mul_f32 v[34:35], v[36:37], v[34:35]
	s_nop 0
	v_cvt_pk_bf16_f32 v41, v34, v35
	global_store_dwordx4 v[42:43], v[38:41], off offset:3328
	v_add_u32_e32 v34, 0xa0, v142
	v_ashrrev_i32_e32 v35, 31, v34
	v_lshlrev_b64 v[36:37], 12, v[34:35]
	v_mad_i64_i32 v[34:35], s[30:31], v34, s77, v[144:145]
	v_lshl_add_u64 v[34:35], v[34:35], 0, v[140:141]
	v_add_co_u32_e32 v34, vcc, s34, v34
	s_nop 1
	v_addc_co_u32_e32 v35, vcc, 0, v35, vcc
	v_mov_b32_e32 v38, v218
	v_mov_b32_e32 v39, v219
	v_mov_b32_e32 v40, v220
	v_mov_b32_e32 v41, v221
	v_lshlrev_b32_e32 v42, 16, v38
	v_and_b32_e32 v43, 0xffff0000, v38
	v_mul_f32_e32 v38, 0xbfb8aa3b, v42
	v_exp_f32_e32 v38, v38
	s_nop 0
	v_add_f32_e32 v38, 1.0, v38
	v_rcp_f32_e32 v44, v38
	v_mul_f32_e32 v38, 0xbfb8aa3b, v43
	v_exp_f32_e32 v38, v38
	s_nop 0
	v_add_f32_e32 v38, 1.0, v38
	v_rcp_f32_e32 v45, v38
	v_lshlrev_b32_e32 v38, 16, v39
	v_and_b32_e32 v39, 0xffff0000, v39
	v_pk_mul_f32 v[42:43], v[44:45], v[42:43]
	s_nop 0
	v_pk_mul_f32 v[30:31], v[30:31], v[42:43]
	s_nop 0
	v_cvt_pk_bf16_f32 v30, v30, v31
	v_mul_f32_e32 v31, 0xbfb8aa3b, v38
	v_exp_f32_e32 v31, v31
	s_nop 0
	v_add_f32_e32 v31, 1.0, v31
	v_rcp_f32_e32 v42, v31
	v_mul_f32_e32 v31, 0xbfb8aa3b, v39
	v_exp_f32_e32 v31, v31
	s_nop 0
	v_add_f32_e32 v31, 1.0, v31
	v_rcp_f32_e32 v43, v31
	s_nop 0
	v_pk_mul_f32 v[38:39], v[42:43], v[38:39]
	s_nop 0
	v_pk_mul_f32 v[32:33], v[32:33], v[38:39]
	s_nop 0
	v_cvt_pk_bf16_f32 v31, v32, v33
	v_lshlrev_b32_e32 v32, 16, v40
	v_and_b32_e32 v33, 0xffff0000, v40
	v_mul_f32_e32 v38, 0xbfb8aa3b, v32
	v_mul_f32_e32 v39, 0xbfb8aa3b, v33
	v_exp_f32_e32 v38, v38
	v_exp_f32_e32 v39, v39
	v_add_f32_e32 v38, 1.0, v38
	v_add_f32_e32 v39, 1.0, v39
	v_rcp_f32_e32 v38, v38
	v_rcp_f32_e32 v39, v39
	s_nop 0
	v_pk_mul_f32 v[32:33], v[38:39], v[32:33]
	s_nop 0
	v_pk_mul_f32 v[26:27], v[26:27], v[32:33]
	s_nop 0
	v_cvt_pk_bf16_f32 v32, v26, v27
	v_lshlrev_b32_e32 v26, 16, v41
	v_mul_f32_e32 v33, 0xbfb8aa3b, v26
	v_exp_f32_e32 v33, v33
	v_and_b32_e32 v27, 0xffff0000, v41
	v_add_f32_e32 v33, 1.0, v33
	v_rcp_f32_e32 v38, v33
	v_mul_f32_e32 v33, 0xbfb8aa3b, v27
	v_exp_f32_e32 v33, v33
	s_nop 0
	v_add_f32_e32 v33, 1.0, v33
	v_rcp_f32_e32 v39, v33
	s_nop 0
	v_pk_mul_f32 v[26:27], v[38:39], v[26:27]
	s_nop 0
	v_pk_mul_f32 v[26:27], v[28:29], v[26:27]
	s_nop 0
	v_cvt_pk_bf16_f32 v33, v26, v27
	v_lshl_add_u64 v[26:27], s[64:65], 0, v[36:37]
	v_lshl_add_u64 v[26:27], v[26:27], 0, v[140:141]
	global_store_dwordx4 v[26:27], v[30:33], off offset:3072
	v_mov_b32_e32 v28, v222
	v_mov_b32_e32 v29, v223
	v_mov_b32_e32 v30, v224
	v_mov_b32_e32 v31, v225
	v_lshlrev_b32_e32 v32, 16, v28
	v_and_b32_e32 v33, 0xffff0000, v28
	v_mul_f32_e32 v28, 0xbfb8aa3b, v32
	v_exp_f32_e32 v28, v28
	s_nop 0
	v_add_f32_e32 v28, 1.0, v28
	v_rcp_f32_e32 v34, v28
	v_mul_f32_e32 v28, 0xbfb8aa3b, v33
	v_exp_f32_e32 v28, v28
	s_nop 0
	v_add_f32_e32 v28, 1.0, v28
	v_rcp_f32_e32 v35, v28
	v_lshlrev_b32_e32 v28, 16, v29
	v_and_b32_e32 v29, 0xffff0000, v29
	v_pk_mul_f32 v[32:33], v[34:35], v[32:33]
	s_nop 0
	v_pk_mul_f32 v[22:23], v[22:23], v[32:33]
	s_nop 0
	v_cvt_pk_bf16_f32 v22, v22, v23
	v_mul_f32_e32 v23, 0xbfb8aa3b, v28
	v_exp_f32_e32 v23, v23
	s_nop 0
	v_add_f32_e32 v23, 1.0, v23
	v_rcp_f32_e32 v32, v23
	v_mul_f32_e32 v23, 0xbfb8aa3b, v29
	v_exp_f32_e32 v23, v23
	s_nop 0
	v_add_f32_e32 v23, 1.0, v23
	v_rcp_f32_e32 v33, v23
	s_nop 0
	v_pk_mul_f32 v[28:29], v[32:33], v[28:29]
	s_nop 0
	v_pk_mul_f32 v[24:25], v[24:25], v[28:29]
	s_nop 0
	v_cvt_pk_bf16_f32 v23, v24, v25
	v_lshlrev_b32_e32 v24, 16, v30
	v_and_b32_e32 v25, 0xffff0000, v30
	v_mul_f32_e32 v28, 0xbfb8aa3b, v24
	v_mul_f32_e32 v29, 0xbfb8aa3b, v25
	v_exp_f32_e32 v28, v28
	v_exp_f32_e32 v29, v29
	v_add_f32_e32 v28, 1.0, v28
	v_add_f32_e32 v29, 1.0, v29
	v_rcp_f32_e32 v28, v28
	v_rcp_f32_e32 v29, v29
	s_nop 0
	v_pk_mul_f32 v[24:25], v[28:29], v[24:25]
	s_nop 0
	v_pk_mul_f32 v[18:19], v[18:19], v[24:25]
	s_nop 0
	v_cvt_pk_bf16_f32 v24, v18, v19
	v_lshlrev_b32_e32 v18, 16, v31
	v_mul_f32_e32 v25, 0xbfb8aa3b, v18
	v_exp_f32_e32 v25, v25
	v_and_b32_e32 v19, 0xffff0000, v31
	v_add_f32_e32 v25, 1.0, v25
	v_rcp_f32_e32 v28, v25
	v_mul_f32_e32 v25, 0xbfb8aa3b, v19
	v_exp_f32_e32 v25, v25
	s_nop 0
	v_add_f32_e32 v25, 1.0, v25
	v_rcp_f32_e32 v29, v25
	s_nop 0
	v_pk_mul_f32 v[18:19], v[28:29], v[18:19]
	s_nop 0
	v_pk_mul_f32 v[18:19], v[20:21], v[18:19]
	s_nop 0
	v_cvt_pk_bf16_f32 v25, v18, v19
	global_store_dwordx4 v[26:27], v[22:25], off offset:3328
	v_add_u32_e32 v18, 0xb0, v142
	v_ashrrev_i32_e32 v19, 31, v18
	v_lshlrev_b64 v[20:21], 12, v[18:19]
	v_mad_i64_i32 v[18:19], s[30:31], v18, s77, v[144:145]
	v_lshl_add_u64 v[18:19], v[18:19], 0, v[140:141]
	v_add_co_u32_e32 v18, vcc, s34, v18
	s_nop 1
	v_addc_co_u32_e32 v19, vcc, 0, v19, vcc
	v_mov_b32_e32 v22, v226
	v_mov_b32_e32 v23, v227
	v_mov_b32_e32 v24, v228
	v_mov_b32_e32 v25, v229
	v_lshlrev_b32_e32 v26, 16, v22
	v_and_b32_e32 v27, 0xffff0000, v22
	v_mul_f32_e32 v22, 0xbfb8aa3b, v26
	v_exp_f32_e32 v22, v22
	s_nop 0
	v_add_f32_e32 v22, 1.0, v22
	v_rcp_f32_e32 v28, v22
	v_mul_f32_e32 v22, 0xbfb8aa3b, v27
	v_exp_f32_e32 v22, v22
	s_nop 0
	v_add_f32_e32 v22, 1.0, v22
	v_rcp_f32_e32 v29, v22
	v_lshlrev_b32_e32 v22, 16, v23
	v_and_b32_e32 v23, 0xffff0000, v23
	v_pk_mul_f32 v[26:27], v[28:29], v[26:27]
	s_nop 0
	v_pk_mul_f32 v[14:15], v[14:15], v[26:27]
	s_nop 0
	v_cvt_pk_bf16_f32 v14, v14, v15
	v_mul_f32_e32 v15, 0xbfb8aa3b, v22
	v_exp_f32_e32 v15, v15
	s_nop 0
	v_add_f32_e32 v15, 1.0, v15
	v_rcp_f32_e32 v26, v15
	v_mul_f32_e32 v15, 0xbfb8aa3b, v23
	v_exp_f32_e32 v15, v15
	s_nop 0
	v_add_f32_e32 v15, 1.0, v15
	v_rcp_f32_e32 v27, v15
	s_nop 0
	v_pk_mul_f32 v[22:23], v[26:27], v[22:23]
	s_nop 0
	v_pk_mul_f32 v[16:17], v[16:17], v[22:23]
	s_nop 0
	v_cvt_pk_bf16_f32 v15, v16, v17
	v_lshlrev_b32_e32 v16, 16, v24
	v_and_b32_e32 v17, 0xffff0000, v24
	v_mul_f32_e32 v22, 0xbfb8aa3b, v16
	v_mul_f32_e32 v23, 0xbfb8aa3b, v17
	v_exp_f32_e32 v22, v22
	v_exp_f32_e32 v23, v23
	v_add_f32_e32 v22, 1.0, v22
	v_add_f32_e32 v23, 1.0, v23
	v_rcp_f32_e32 v22, v22
	v_rcp_f32_e32 v23, v23
	s_nop 0
	v_pk_mul_f32 v[16:17], v[22:23], v[16:17]
	s_nop 0
	v_pk_mul_f32 v[10:11], v[10:11], v[16:17]
	s_nop 0
	v_cvt_pk_bf16_f32 v16, v10, v11
	v_lshlrev_b32_e32 v10, 16, v25
	v_mul_f32_e32 v17, 0xbfb8aa3b, v10
	v_exp_f32_e32 v17, v17
	v_and_b32_e32 v11, 0xffff0000, v25
	v_add_f32_e32 v17, 1.0, v17
	v_rcp_f32_e32 v22, v17
	v_mul_f32_e32 v17, 0xbfb8aa3b, v11
	v_exp_f32_e32 v17, v17
	s_nop 0
	v_add_f32_e32 v17, 1.0, v17
	v_rcp_f32_e32 v23, v17
	s_nop 0
	v_pk_mul_f32 v[10:11], v[22:23], v[10:11]
	s_nop 0
	v_pk_mul_f32 v[10:11], v[12:13], v[10:11]
	s_nop 0
	v_cvt_pk_bf16_f32 v17, v10, v11
	v_lshl_add_u64 v[10:11], s[64:65], 0, v[20:21]
	v_lshl_add_u64 v[10:11], v[10:11], 0, v[140:141]
	global_store_dwordx4 v[10:11], v[14:17], off offset:3072
	v_mov_b32_e32 v12, v230
	v_mov_b32_e32 v13, v231
	v_mov_b32_e32 v14, v232
	v_mov_b32_e32 v15, v233
	v_lshlrev_b32_e32 v16, 16, v12
	v_and_b32_e32 v17, 0xffff0000, v12
	v_mul_f32_e32 v12, 0xbfb8aa3b, v16
	v_exp_f32_e32 v12, v12
	s_nop 0
	v_add_f32_e32 v12, 1.0, v12
	v_rcp_f32_e32 v18, v12
	v_mul_f32_e32 v12, 0xbfb8aa3b, v17
	v_exp_f32_e32 v12, v12
	s_nop 0
	v_add_f32_e32 v12, 1.0, v12
	v_rcp_f32_e32 v19, v12
	v_lshlrev_b32_e32 v12, 16, v13
	v_and_b32_e32 v13, 0xffff0000, v13
	v_pk_mul_f32 v[16:17], v[18:19], v[16:17]
	s_nop 0
	v_pk_mul_f32 v[6:7], v[6:7], v[16:17]
	s_nop 0
	v_cvt_pk_bf16_f32 v6, v6, v7
	v_mul_f32_e32 v7, 0xbfb8aa3b, v12
	v_exp_f32_e32 v7, v7
	s_nop 0
	v_add_f32_e32 v7, 1.0, v7
	v_rcp_f32_e32 v16, v7
	v_mul_f32_e32 v7, 0xbfb8aa3b, v13
	v_exp_f32_e32 v7, v7
	s_nop 0
	v_add_f32_e32 v7, 1.0, v7
	v_rcp_f32_e32 v17, v7
	s_nop 0
	v_pk_mul_f32 v[12:13], v[16:17], v[12:13]
	s_nop 0
	v_pk_mul_f32 v[8:9], v[8:9], v[12:13]
	s_nop 0
	v_cvt_pk_bf16_f32 v7, v8, v9
	v_lshlrev_b32_e32 v8, 16, v14
	v_and_b32_e32 v9, 0xffff0000, v14
	v_mul_f32_e32 v12, 0xbfb8aa3b, v8
	v_mul_f32_e32 v13, 0xbfb8aa3b, v9
	v_exp_f32_e32 v12, v12
	v_exp_f32_e32 v13, v13
	v_add_f32_e32 v12, 1.0, v12
	v_add_f32_e32 v13, 1.0, v13
	v_rcp_f32_e32 v12, v12
	v_rcp_f32_e32 v13, v13
	s_nop 0
	v_pk_mul_f32 v[8:9], v[12:13], v[8:9]
	s_nop 0
	v_pk_mul_f32 v[2:3], v[2:3], v[8:9]
	s_nop 0
	v_cvt_pk_bf16_f32 v8, v2, v3
	v_lshlrev_b32_e32 v2, 16, v15
	v_mul_f32_e32 v9, 0xbfb8aa3b, v2
	v_exp_f32_e32 v9, v9
	v_and_b32_e32 v3, 0xffff0000, v15
	v_add_f32_e32 v9, 1.0, v9
	v_rcp_f32_e32 v12, v9
	v_mul_f32_e32 v9, 0xbfb8aa3b, v3
	v_exp_f32_e32 v9, v9
	s_nop 0
	v_add_f32_e32 v9, 1.0, v9
	v_rcp_f32_e32 v13, v9
	s_nop 0
	v_pk_mul_f32 v[2:3], v[12:13], v[2:3]
	s_nop 0
	v_pk_mul_f32 v[2:3], v[4:5], v[2:3]
	s_nop 0
	v_cvt_pk_bf16_f32 v9, v2, v3
	global_store_dwordx4 v[10:11], v[6:9], off offset:3328
	s_and_b64 vcc, exec, s[36:37]
	s_mov_b32 s62, s80
	s_mov_b32 s81, s18
	s_mov_b64 s[38:39], s[40:41]
	s_mov_b64 s[30:31], s[0:1]
	s_cbranch_vccnz .LBB0_739
